# attention loads via SGPR base + single V write address (on top of v15)
# baseline (speedup 1.0000x reference)
.LBB0_338:
	s_or_b64 exec, exec, s[12:13]
	v_mov_b32_e32 v51, s43
	v_mov_b32_e32 v56, s42
	v_cmp_gt_i32_e64 s[12:13], 0, v185
	s_nop 1
	v_max_f32_e32 v57, v18, v18
	v_mov_b32_e32 v190, 0
	v_cndmask_b32_e64 v51, v51, v56, s[12:13]
	v_cndmask_b32_e64 v56, v51, 0, s[8:9]
	v_max_f32_e32 v51, v19, v19
	v_max_f32_e32 v51, v57, v51
	v_max3_f32 v51, v51, v20, v21
	v_max3_f32 v51, v51, v22, v23
	v_max3_f32 v51, v51, v24, v25
	v_max3_f32 v51, v51, v26, v27
	v_max3_f32 v51, v51, v28, v29
	v_max3_f32 v51, v51, v30, v31
	v_max3_f32 v51, v51, v32, v33
	v_max3_f32 v51, v51, v2, v3
	v_max3_f32 v51, v51, v4, v5
	v_max3_f32 v51, v51, v6, v7
	v_max3_f32 v51, v51, v8, v9
	v_max3_f32 v51, v51, v10, v11
	v_max3_f32 v51, v51, v12, v13
	v_max3_f32 v51, v51, v14, v15
	v_max3_f32 v51, v51, v16, v17
	v_mov_b32_e32 v57, v51
	s_nop 1
	v_permlane32_swap_b32_e32 v51, v57
	v_max_f32_e32 v57, v57, v57
	v_max_f32_e32 v51, v51, v51
	v_max_f32_e32 v51, v51, v57
	v_add_f32_e32 v57, v56, v51
	v_sub_f32_e32 v191, s43, v57
	v_sub_f32_e32 v190, 0, v57
	v_sub_f32_e32 v192, s42, v57
	v_mov_b32_e32 v176, 0
	v_readfirstlane_b32 s98, v185
	s_mov_b32 s99, 64
	v_sub_f32_e32 v56, v56, v57
	v_add_f32_e32 v3, v3, v56
	v_add_f32_e32 v2, v2, v56
	v_add_f32_e32 v4, v4, v56
	v_exp_f32_e32 v196, v3
	v_lshlrev_b32_e32 v3, 4, v55
	s_xor_b64 s[42:43], s[2:3], -1
	v_exp_f32_e32 v195, v2
	v_exp_f32_e32 v197, v4
	v_lshlrev_b32_e32 v2, 3, v55
	v_and_b32_e32 v3, 0xc0, v3
	v_lshlrev_b32_e32 v4, 1, v55
	v_and_or_b32 v3, v2, 24, v3
	v_and_b32_e32 v4, 32, v4
	v_and_b32_e32 v2, 0x100, v2
	s_cmp_lg_u32 0, -1
	v_or3_b32 v2, v3, v4, v2
	s_cselect_b32 s2, 0, 0
	v_add_u32_e32 v180, s2, v2
	s_addk_i32 s2, 0x4000
	v_add_u32_e32 v177, s2, v2
	v_add_lshl_u32 v2, v185, v53, 2
	v_ashrrev_i32_e32 v51, 31, v50
	v_add_f32_e32 v18, v18, v56
	v_add_f32_e32 v19, v19, v56
	v_add_f32_e32 v20, v20, v56
	v_add_f32_e32 v21, v21, v56
	v_add_f32_e32 v22, v22, v56
	v_add_f32_e32 v23, v23, v56
	v_add_f32_e32 v24, v24, v56
	v_add_f32_e32 v25, v25, v56
	v_add_f32_e32 v26, v26, v56
	v_add_f32_e32 v27, v27, v56
	v_add_f32_e32 v28, v28, v56
	v_add_f32_e32 v29, v29, v56
	v_add_f32_e32 v30, v30, v56
	v_add_f32_e32 v31, v31, v56
	v_add_f32_e32 v32, v32, v56
	v_add_f32_e32 v33, v33, v56
	v_add_f32_e32 v5, v5, v56
	v_add_f32_e32 v6, v6, v56
	v_add_f32_e32 v7, v7, v56
	v_add_f32_e32 v8, v8, v56
	v_add_f32_e32 v9, v9, v56
	v_add_f32_e32 v10, v10, v56
	v_add_f32_e32 v11, v11, v56
	v_add_f32_e32 v12, v12, v56
	v_add_f32_e32 v13, v13, v56
	v_add_f32_e32 v14, v14, v56
	v_add_f32_e32 v15, v15, v56
	v_add_f32_e32 v16, v16, v56
	v_add_f32_e32 v17, v17, v56
	v_sub_u32_e32 v2, v98, v2
	s_add_i32 s2, 0, 0x10c80
	v_exp_f32_e32 v199, v18
	v_exp_f32_e32 v201, v19
	v_exp_f32_e32 v202, v20
	v_exp_f32_e32 v205, v21
	v_exp_f32_e32 v207, v22
	v_exp_f32_e32 v209, v23
	v_exp_f32_e32 v211, v24
	v_exp_f32_e32 v213, v25
	v_exp_f32_e32 v215, v26
	v_exp_f32_e32 v216, v27
	v_exp_f32_e32 v217, v28
	v_exp_f32_e32 v218, v29
	v_exp_f32_e32 v221, v30
	v_exp_f32_e32 v222, v31
	v_exp_f32_e32 v223, v32
	v_exp_f32_e32 v224, v33
	v_exp_f32_e32 v198, v5
	v_exp_f32_e32 v200, v6
	v_exp_f32_e32 v203, v7
	v_exp_f32_e32 v204, v8
	v_exp_f32_e32 v206, v9
	v_exp_f32_e32 v208, v10
	v_exp_f32_e32 v210, v11
	v_exp_f32_e32 v212, v12
	v_exp_f32_e32 v214, v13
	v_exp_f32_e32 v150, v14
	v_exp_f32_e32 v151, v15
	v_exp_f32_e32 v152, v16
	v_exp_f32_e32 v153, v17
	v_add_u32_e32 v194, s2, v2
	v_lshl_add_u64 v[2:3], s[30:31], 0, v[50:51]
	s_waitcnt vmcnt(0)
	v_mad_u64_u32 v[4:5], s[2:3], v2, s49, 0
	v_and_b32_e32 v2, 15, v52
	v_mad_i32_i24 v3, v3, s49, v5
	v_lshl_or_b32 v2, v2, 4, v4
	s_mov_b32 s82, 0
	s_waitcnt vmcnt(3)
	ds_write_b128 v183, v[34:37] offset:16384
	s_waitcnt vmcnt(2)
	ds_write_b128 v184, v[38:41] offset:16384
	s_waitcnt vmcnt(1)
	ds_write_b128 v181, v[42:45] offset:49152
	s_waitcnt vmcnt(0)
	ds_write_b128 v182, v[46:49] offset:49152
	v_mov_b32_e32 v181, v180
	s_mov_b32 s54, 0
	s_movk_i32 s55, 0x4000
	s_mov_b32 s56, 0x12000
	v_sub_u32_e32 v193, s81, v54
	s_mov_b32 s83, 2
	v_lshl_add_u64 v[160:161], s[40:41], 0, v[2:3]
	s_and_b32 s100, s42, 0x80
	v_lshrrev_b32_e32 v2, 3, v52
	v_sub_u32_e32 v3, v2, v50
	v_mul_u32_u24_e32 v3, 0x2800, v3
	v_and_b32_e32 v4, 8, v52
	v_lshlrev_b32_e32 v4, 4, v4
	v_sub_u32_e32 v3, v3, v4
	v_add_u32_e32 v3, s100, v3
	v_readfirstlane_b32 s101, v50
	v_readfirstlane_b32 s12, v160
	v_readfirstlane_b32 s13, v161
	s_nop 1
	v_subrev_u32_e32 v4, s101, v50
	v_mul_u32_u24_e32 v4, 0x2800, v4
	v_and_b32_e32 v160, 15, v52
	v_lshl_add_u32 v160, v160, 4, v4
	v_add_u32_e32 v161, 0x50000, v160
	v_add_u32_e32 v252, v160, v3
	v_and_b32_e32 v3, 7, v52
	v_and_b32_e32 v4, 7, v2
	v_xor_b32_e32 v3, v3, v4
	v_lshlrev_b32_e32 v3, 4, v3
	v_lshl_or_b32 v235, v2, 8, v3
	v_add_u32_e32 v235, s100, v235
	v_mov_b32_e32 v2, 0
	v_mov_b32_e32 v3, v176
	v_mov_b32_e32 v4, v176
	v_mov_b32_e32 v5, v176
	v_mov_b32_e32 v6, v176
	v_mov_b32_e32 v7, v176
	v_mov_b32_e32 v8, v176
	v_mov_b32_e32 v9, v176
	v_mov_b32_e32 v10, v176
	v_mov_b32_e32 v11, v176
	v_mov_b32_e32 v12, v176
	v_mov_b32_e32 v13, v176
	v_mov_b32_e32 v14, v176
	v_mov_b32_e32 v15, v176
	v_mov_b32_e32 v16, v176
	v_mov_b32_e32 v17, v176
	v_mov_b32_e32 v18, 0
	v_mov_b32_e32 v19, v176
	v_mov_b32_e32 v20, v176
	v_mov_b32_e32 v21, v176
	v_mov_b32_e32 v22, v176
	v_mov_b32_e32 v23, v176
	v_mov_b32_e32 v24, v176
	v_mov_b32_e32 v25, v176
	v_mov_b32_e32 v26, v176
	v_mov_b32_e32 v27, v176
	v_mov_b32_e32 v28, v176
	v_mov_b32_e32 v29, v176
	v_mov_b32_e32 v30, v176
	v_mov_b32_e32 v31, v176
	v_mov_b32_e32 v32, v176
	v_mov_b32_e32 v33, v176
	v_mov_b32_e32 v34, 0
	v_mov_b32_e32 v35, v176
	v_mov_b32_e32 v36, v176
	v_mov_b32_e32 v37, v176
	v_mov_b32_e32 v38, v176
	v_mov_b32_e32 v39, v176
	v_mov_b32_e32 v40, v176
	v_mov_b32_e32 v41, v176
	v_mov_b32_e32 v42, v176
	v_mov_b32_e32 v43, v176
	v_mov_b32_e32 v44, v176
	v_mov_b32_e32 v45, v176
	v_mov_b32_e32 v46, v176
	v_mov_b32_e32 v47, v176
	v_mov_b32_e32 v48, v176
	v_mov_b32_e32 v49, v176
	v_mov_b32_e32 v50, 0
	v_mov_b32_e32 v51, v176
	v_mov_b32_e32 v52, v176
	v_mov_b32_e32 v53, v176
	v_mov_b32_e32 v54, v176
	v_mov_b32_e32 v55, v176
	v_mov_b32_e32 v56, v176
	v_mov_b32_e32 v57, v176
	v_mov_b32_e32 v58, v176
	v_mov_b32_e32 v59, v176
	v_mov_b32_e32 v60, v176
	v_mov_b32_e32 v61, v176
	v_mov_b32_e32 v62, v176
	v_mov_b32_e32 v63, v176
	v_mov_b32_e32 v64, v176
	v_mov_b32_e32 v65, v176
	s_waitcnt lgkmcnt(0)
	s_barrier
	s_branch .LBB0_346
.LBB0_345:
	s_or_b64 exec, exec, s[2:3]
	v_add_u32_e32 v177, s54, v181
	v_add_f32_e32 v176, v176, v219
	ds_read_b64_tr_b16 v[196:197], v177 offset:0
	ds_read_b64_tr_b16 v[198:199], v177 offset:0x800
	ds_read_b64_tr_b16 v[200:201], v177 offset:0x1000
	ds_read_b64_tr_b16 v[202:203], v177 offset:0x1800
	ds_read_b64_tr_b16 v[206:207], v177 offset:0x2000
	ds_read_b64_tr_b16 v[208:209], v177 offset:0x2800
	ds_read_b64_tr_b16 v[210:211], v177 offset:0x3000
	ds_read_b64_tr_b16 v[212:213], v177 offset:0x3800
	s_waitcnt lgkmcnt(0)
	v_add_f32_e32 v176, v176, v98
	v_mfma_f32_32x32x16_bf16 v[50:65], v[150:153], v[196:199], v[50:65]
	v_exp_f32_e32 v195, v66
	v_exp_f32_e32 v196, v67
	ds_read_b64_tr_b16 v[66:67], v177 offset:0x200
	v_exp_f32_e32 v197, v68
	v_exp_f32_e32 v198, v69
	ds_read_b64_tr_b16 v[68:69], v177 offset:0xa00
	v_exp_f32_e32 v199, v82
	v_mfma_f32_32x32x16_bf16 v[50:65], v[134:137], v[200:203], v[50:65]
	v_exp_f32_e32 v201, v83
	ds_read_b64_tr_b16 v[82:83], v177 offset:0x1200
	v_exp_f32_e32 v202, v84
	v_exp_f32_e32 v205, v85
	ds_read_b64_tr_b16 v[84:85], v177 offset:0x1a00
	ds_read_b64_tr_b16 v[214:215], v177 offset:0x2200
	ds_read_b64_tr_b16 v[216:217], v177 offset:0x2a00
	v_mfma_f32_32x32x16_bf16 v[50:65], v[130:133], v[206:209], v[50:65]
	ds_read_b64_tr_b16 v[218:219], v177 offset:0x3200
	ds_read_b64_tr_b16 v[220:221], v177 offset:0x3a00
	s_waitcnt lgkmcnt(0)
	v_mfma_f32_32x32x16_bf16 v[50:65], v[126:129], v[210:213], v[50:65]
	v_mfma_f32_32x32x16_bf16 v[34:49], v[150:153], v[66:69], v[34:49]
	ds_read_b64_tr_b16 v[66:67], v177 offset:0x400
	ds_read_b64_tr_b16 v[68:69], v177 offset:0xc00
	v_exp_f32_e32 v200, v70
	v_exp_f32_e32 v203, v71
	ds_read_b64_tr_b16 v[70:71], v177 offset:0x1400
	v_exp_f32_e32 v204, v72
	v_exp_f32_e32 v206, v73
	v_mfma_f32_32x32x16_bf16 v[34:49], v[134:137], v[82:85], v[34:49]
	ds_read_b64_tr_b16 v[72:73], v177 offset:0x1c00
	ds_read_b64_tr_b16 v[82:83], v177 offset:0x2400
	ds_read_b64_tr_b16 v[84:85], v177 offset:0x2c00
	v_exp_f32_e32 v207, v86
	v_exp_f32_e32 v209, v87
	ds_read_b64_tr_b16 v[86:87], v177 offset:0x3400
	v_exp_f32_e32 v211, v88
	v_mfma_f32_32x32x16_bf16 v[34:49], v[130:133], v[214:217], v[34:49]
	v_exp_f32_e32 v213, v89
	ds_read_b64_tr_b16 v[88:89], v177 offset:0x3c00
	s_waitcnt lgkmcnt(0)
	v_mfma_f32_32x32x16_bf16 v[34:49], v[126:129], v[218:221], v[34:49]
	v_mfma_f32_32x32x16_bf16 v[18:33], v[150:153], v[66:69], v[18:33]
	ds_read_b64_tr_b16 v[66:67], v177 offset:0x600
	ds_read_b64_tr_b16 v[68:69], v177 offset:0xe00
	v_exp_f32_e32 v208, v74
	v_exp_f32_e32 v210, v75
	v_exp_f32_e32 v212, v76
	v_exp_f32_e32 v214, v77
	v_exp_f32_e32 v215, v90
	v_mfma_f32_32x32x16_bf16 v[18:33], v[134:137], v[70:73], v[18:33]
	ds_read_b64_tr_b16 v[70:71], v177 offset:0x1600
	ds_read_b64_tr_b16 v[72:73], v177 offset:0x1e00
	ds_read_b64_tr_b16 v[74:75], v177 offset:0x2600
	ds_read_b64_tr_b16 v[76:77], v177 offset:0x2e00
	v_exp_f32_e32 v216, v91
	v_exp_f32_e32 v217, v92
	v_exp_f32_e32 v218, v93
	v_mfma_f32_32x32x16_bf16 v[18:33], v[130:133], v[82:85], v[18:33]
	ds_read_b64_tr_b16 v[82:83], v177 offset:0x3600
	ds_read_b64_tr_b16 v[84:85], v177 offset:0x3e00
	s_waitcnt lgkmcnt(0)
	v_mfma_f32_32x32x16_bf16 v[18:33], v[126:129], v[86:89], v[18:33]
	v_mfma_f32_32x32x16_bf16 v[2:17], v[150:153], v[66:69], v[2:17]
	v_exp_f32_e32 v221, v94
	v_exp_f32_e32 v150, v78
	v_exp_f32_e32 v222, v95
	v_exp_f32_e32 v151, v79
	v_exp_f32_e32 v223, v96
	v_exp_f32_e32 v152, v80
	v_exp_f32_e32 v224, v97
	v_mfma_f32_32x32x16_bf16 v[2:17], v[134:137], v[70:73], v[2:17]
	v_exp_f32_e32 v153, v81
	v_add_u32_e32 v182, s56, v183
	s_add_i32 s83, s83, 2
	v_add_u32_e32 v194, 0x200, v194
	v_mfma_f32_32x32x16_bf16 v[2:17], v[130:133], v[74:77], v[2:17]
	s_waitcnt vmcnt(0)
	ds_write_b128 v235, v[142:145] offset:49152
	ds_write_b128 v182, v[138:141]
	ds_write_b128 v182, v[154:157] offset:8192
	s_mov_b32 s80, s54
	s_mov_b32 s54, s55
	s_mov_b32 s55, s56
	s_mov_b32 s56, s80
	s_cmp_ge_u32 s83, s78
	s_waitcnt lgkmcnt(0)
	s_barrier
	v_mfma_f32_32x32x16_bf16 v[2:17], v[126:129], v[82:85], v[2:17]
	s_cbranch_scc1 .LBB0_350

.Lattn_back_a:
	ds_read_b128 v[126:129], v186 offset:49152
	ds_read_b128 v[130:133], v186 offset:57344
	v_add_f32_e32 v98, 0, v199
	v_add_f32_e32 v98, v201, v98
	v_add_f32_e32 v98, v202, v98
	v_add_f32_e32 v98, v205, v98
	v_add_f32_e32 v98, v207, v98
	v_add_f32_e32 v98, v209, v98
	s_waitcnt lgkmcnt(1)
	v_mfma_f32_32x32x16_bf16 v[82:97], v[126:129], v[118:121], v[236:251]
	v_add_f32_e32 v98, v211, v98
	v_add_f32_e32 v98, v213, v98
	v_add_f32_e32 v98, v215, v98
	ds_read_b128 v[134:137], v187 offset:49152
	ds_read_b128 v[138:141], v187 offset:57344
	ds_read_b128 v[142:145], v188 offset:49152
	ds_read_b128 v[146:149], v188 offset:57344
	ds_read_b128 v[154:157], v189 offset:49152
	ds_read_b128 v[226:229], v189 offset:57344
	v_add_f32_e32 v98, v216, v98
	v_add_f32_e32 v98, v217, v98
	v_add_f32_e32 v98, v218, v98
	s_waitcnt lgkmcnt(6)
	v_mfma_f32_32x32x16_bf16 v[66:81], v[130:133], v[118:121], v[236:251]
	v_add_f32_e32 v98, v221, v98
	v_add_f32_e32 v98, v222, v98
	v_add_f32_e32 v98, v223, v98
	v_add_f32_e32 v98, v224, v98
	v_add_f32_e32 v98, v195, v98
	v_add_f32_e32 v98, v196, v98
	v_add_f32_e32 v98, v197, v98
	s_waitcnt lgkmcnt(5)
	v_mfma_f32_32x32x16_bf16 v[82:97], v[134:137], v[114:117], v[82:97]
	v_add_f32_e32 v98, v198, v98
	v_add_f32_e32 v98, v200, v98
	v_add_f32_e32 v98, v203, v98
	v_add_f32_e32 v98, v204, v98
	v_add_f32_e32 v98, v206, v98
	v_add_f32_e32 v98, v208, v98
	v_add_f32_e32 v98, v210, v98
	s_waitcnt lgkmcnt(4)
	v_mfma_f32_32x32x16_bf16 v[66:81], v[138:141], v[114:117], v[66:81]
	v_add_f32_e32 v98, v212, v98
	v_add_f32_e32 v98, v214, v98
	v_add_f32_e32 v98, v150, v98
	v_add_f32_e32 v98, v151, v98
	v_add_f32_e32 v98, v152, v98
	v_add_f32_e32 v219, v153, v98
	s_waitcnt lgkmcnt(3)
	v_mfma_f32_32x32x16_bf16 v[82:97], v[142:145], v[110:113], v[82:97]
	v_cvt_pk_bf16_f32 v134, v199, v201
	v_cvt_pk_bf16_f32 v135, v202, v205
	v_cvt_pk_bf16_f32 v136, v207, v209
	v_cvt_pk_bf16_f32 v137, v211, v213
	v_cvt_pk_bf16_f32 v138, v215, v216
	s_waitcnt lgkmcnt(2)
	v_mfma_f32_32x32x16_bf16 v[66:81], v[146:149], v[110:113], v[66:81]
	v_cvt_pk_bf16_f32 v139, v217, v218
	v_cvt_pk_bf16_f32 v140, v221, v222
	v_cvt_pk_bf16_f32 v141, v223, v224
	v_cvt_pk_bf16_f32 v126, v195, v196
	v_cvt_pk_bf16_f32 v127, v197, v198
	v_cvt_pk_bf16_f32 v128, v200, v203
	v_cvt_pk_bf16_f32 v129, v204, v206
	s_waitcnt lgkmcnt(1)
	v_mfma_f32_32x32x16_bf16 v[82:97], v[154:157], v[106:109], v[82:97]
	v_cvt_pk_bf16_f32 v130, v208, v210
	v_cvt_pk_bf16_f32 v131, v212, v214
	v_cvt_pk_bf16_f32 v132, v150, v151
	v_cvt_pk_bf16_f32 v133, v152, v153
	s_waitcnt lgkmcnt(0)
	v_mfma_f32_32x32x16_bf16 v[66:81], v[226:229], v[106:109], v[66:81]
	global_load_dwordx4 v[142:145], v160, s[12:13] offset:2048
	global_load_dwordx4 v[146:149], v252, s[12:13]
	global_load_dwordx4 v[154:157], v161, s[12:13] offset:2048
	s_and_saveexec_b64 s[2:3], s[8:9]
	s_cbranch_execz .LBB0_348
	ds_read2_b32 v[196:197], v194 offset1:1
	ds_read2_b32 v[198:199], v194 offset0:16 offset1:17
	ds_read2_b32 v[200:201], v194 offset0:18 offset1:19
	ds_read2_b32 v[202:203], v194 offset0:24 offset1:25
	ds_read2_b32 v[204:205], v194 offset0:26 offset1:27
	ds_read2_b32 v[206:207], v194 offset0:2 offset1:3
	ds_read2_b32 v[208:209], v194 offset0:8 offset1:9
	ds_read2_b32 v[210:211], v194 offset0:10 offset1:11
	s_waitcnt lgkmcnt(7)
	v_pk_add_f32 v[82:83], v[82:83], v[196:197]
	s_waitcnt lgkmcnt(3)
	v_pk_add_f32 v[96:97], v[96:97], v[204:205]
	v_pk_add_f32 v[94:95], v[94:95], v[202:203]
	v_pk_add_f32 v[92:93], v[92:93], v[200:201]
	v_pk_add_f32 v[90:91], v[90:91], v[198:199]
	s_waitcnt lgkmcnt(0)
	v_pk_add_f32 v[88:89], v[88:89], v[210:211]
	v_pk_add_f32 v[86:87], v[86:87], v[208:209]
	v_pk_add_f32 v[84:85], v[84:85], v[206:207]
	ds_read2_b32 v[196:197], v194 offset0:48 offset1:49
	ds_read2_b32 v[198:199], v194 offset0:50 offset1:51
	ds_read2_b32 v[200:201], v194 offset0:56 offset1:57
	ds_read2_b32 v[202:203], v194 offset0:58 offset1:59
	ds_read2_b32 v[204:205], v194 offset0:32 offset1:33
	ds_read2_b32 v[206:207], v194 offset0:34 offset1:35
	ds_read2_b32 v[208:209], v194 offset0:40 offset1:41
	ds_read2_b32 v[210:211], v194 offset0:42 offset1:43
	s_waitcnt lgkmcnt(4)
	v_pk_add_f32 v[80:81], v[80:81], v[202:203]
	v_pk_add_f32 v[78:79], v[78:79], v[200:201]
	v_pk_add_f32 v[76:77], v[76:77], v[198:199]
	v_pk_add_f32 v[74:75], v[74:75], v[196:197]
	s_waitcnt lgkmcnt(0)
	v_pk_add_f32 v[72:73], v[72:73], v[210:211]
	v_pk_add_f32 v[70:71], v[70:71], v[208:209]
	v_pk_add_f32 v[68:69], v[68:69], v[206:207]
	v_pk_add_f32 v[66:67], v[66:67], v[204:205]
.LBB0_348:
	s_or_b64 exec, exec, s[2:3]
	v_add_u32_e32 v180, s54, v181
	ds_read_b64_tr_b16 v[196:197], v180 offset:0
	ds_read_b64_tr_b16 v[198:199], v180 offset:0x800
	ds_read_b64_tr_b16 v[200:201], v180 offset:0x1000
	ds_read_b64_tr_b16 v[202:203], v180 offset:0x1800
	ds_read_b64_tr_b16 v[204:205], v180 offset:0x2000
	ds_read_b64_tr_b16 v[206:207], v180 offset:0x2800
	ds_read_b64_tr_b16 v[208:209], v180 offset:0x3000
	ds_read_b64_tr_b16 v[210:211], v180 offset:0x3800
	s_waitcnt lgkmcnt(0)
	s_addk_i32 s82, 0x80
	v_mfma_f32_32x32x16_bf16 v[50:65], v[134:137], v[196:199], v[50:65]
	v_exp_f32_e32 v213, v66
	v_exp_f32_e32 v215, v67
	ds_read_b64_tr_b16 v[66:67], v180 offset:0x200
	v_exp_f32_e32 v217, v68
	v_exp_f32_e32 v221, v69
	ds_read_b64_tr_b16 v[68:69], v180 offset:0xa00
	v_exp_f32_e32 v212, v82
	v_mfma_f32_32x32x16_bf16 v[50:65], v[138:141], v[200:203], v[50:65]
	v_exp_f32_e32 v214, v83
	ds_read_b64_tr_b16 v[82:83], v180 offset:0x1200
	v_exp_f32_e32 v216, v84
	v_exp_f32_e32 v218, v85
	ds_read_b64_tr_b16 v[84:85], v180 offset:0x1a00
	ds_read_b64_tr_b16 v[196:197], v180 offset:0x2200
	ds_read_b64_tr_b16 v[198:199], v180 offset:0x2a00
	v_mfma_f32_32x32x16_bf16 v[50:65], v[126:129], v[204:207], v[50:65]
	ds_read_b64_tr_b16 v[200:201], v180 offset:0x3200
	ds_read_b64_tr_b16 v[202:203], v180 offset:0x3a00
	s_waitcnt lgkmcnt(0)
	v_mfma_f32_32x32x16_bf16 v[50:65], v[130:133], v[208:211], v[50:65]
	v_mfma_f32_32x32x16_bf16 v[34:49], v[134:137], v[66:69], v[34:49]
	ds_read_b64_tr_b16 v[66:67], v180 offset:0x400
	ds_read_b64_tr_b16 v[68:69], v180 offset:0xc00
	v_exp_f32_e32 v205, v70
	v_exp_f32_e32 v207, v71
	ds_read_b64_tr_b16 v[70:71], v180 offset:0x1400
	v_exp_f32_e32 v209, v72
	v_exp_f32_e32 v211, v73
	v_mfma_f32_32x32x16_bf16 v[34:49], v[138:141], v[82:85], v[34:49]
	ds_read_b64_tr_b16 v[72:73], v180 offset:0x1c00
	ds_read_b64_tr_b16 v[82:83], v180 offset:0x2400
	ds_read_b64_tr_b16 v[84:85], v180 offset:0x2c00
	v_exp_f32_e32 v204, v86
	v_exp_f32_e32 v206, v87
	ds_read_b64_tr_b16 v[86:87], v180 offset:0x3400
	v_exp_f32_e32 v208, v88
	v_mfma_f32_32x32x16_bf16 v[34:49], v[126:129], v[196:199], v[34:49]
	v_exp_f32_e32 v210, v89
	ds_read_b64_tr_b16 v[88:89], v180 offset:0x3c00
	s_waitcnt lgkmcnt(0)
	v_mfma_f32_32x32x16_bf16 v[34:49], v[130:133], v[200:203], v[34:49]
	v_mfma_f32_32x32x16_bf16 v[18:33], v[134:137], v[66:69], v[18:33]
	ds_read_b64_tr_b16 v[66:67], v180 offset:0x600
	ds_read_b64_tr_b16 v[68:69], v180 offset:0xe00
	v_exp_f32_e32 v197, v74
	v_exp_f32_e32 v199, v75
	v_exp_f32_e32 v201, v76
	v_exp_f32_e32 v203, v77
	v_exp_f32_e32 v196, v90
	v_mfma_f32_32x32x16_bf16 v[18:33], v[138:141], v[70:73], v[18:33]
	ds_read_b64_tr_b16 v[70:71], v180 offset:0x1600
	ds_read_b64_tr_b16 v[72:73], v180 offset:0x1e00
	ds_read_b64_tr_b16 v[74:75], v180 offset:0x2600
	ds_read_b64_tr_b16 v[76:77], v180 offset:0x2e00
	v_exp_f32_e32 v198, v91
	v_exp_f32_e32 v200, v92
	v_exp_f32_e32 v202, v93
	v_mfma_f32_32x32x16_bf16 v[18:33], v[126:129], v[82:85], v[18:33]
	ds_read_b64_tr_b16 v[82:83], v180 offset:0x3600
	ds_read_b64_tr_b16 v[84:85], v180 offset:0x3e00
	s_waitcnt lgkmcnt(0)
	v_mfma_f32_32x32x16_bf16 v[18:33], v[130:133], v[86:89], v[18:33]
	v_mfma_f32_32x32x16_bf16 v[2:17], v[134:137], v[66:69], v[2:17]
	v_add_u32_e32 v182, s56, v183
	v_exp_f32_e32 v222, v94
	v_exp_f32_e32 v223, v78
	v_exp_f32_e32 v224, v95
	v_mfma_f32_32x32x16_bf16 v[2:17], v[138:141], v[70:73], v[2:17]
	v_exp_f32_e32 v226, v79
	v_exp_f32_e32 v227, v96
	v_exp_f32_e32 v228, v80
	v_exp_f32_e32 v229, v97
	v_exp_f32_e32 v230, v81
	s_waitcnt vmcnt(0)
	ds_write_b128 v235, v[146:149] offset:32768
	ds_write_b128 v182, v[142:145]
	ds_write_b128 v182, v[154:157] offset:8192
	s_waitcnt lgkmcnt(0)
	v_mfma_f32_32x32x16_bf16 v[2:17], v[126:129], v[74:77], v[2:17]
	s_barrier
	v_mfma_f32_32x32x16_bf16 v[2:17], v[130:133], v[82:85], v[2:17]
	s_mov_b32 s80, s54
	s_mov_b32 s54, s55
	s_mov_b32 s55, s56
	s_mov_b32 s56, s80
	s_cmp_eq_u32 s82, s99
	s_cbranch_scc1 .Lattn_refill_b
.Lattn_back_b:
	ds_read_b128 v[126:129], v186 offset:32768
	ds_read_b128 v[130:133], v186 offset:40960
	ds_read_b128 v[134:137], v187 offset:32768
	ds_read_b128 v[138:141], v187 offset:40960
	v_add_f32_e32 v98, 0, v212
	v_add_f32_e32 v98, v214, v98
	v_add_f32_e32 v98, v216, v98
	v_add_f32_e32 v98, v218, v98
	v_add_f32_e32 v98, v204, v98
	v_add_f32_e32 v98, v206, v98
	v_add_f32_e32 v98, v208, v98
	s_waitcnt lgkmcnt(3)
	v_mfma_f32_32x32x16_bf16 v[82:97], v[126:129], v[118:121], v[236:251]
	v_add_f32_e32 v98, v210, v98
	v_add_f32_e32 v98, v196, v98
	v_add_f32_e32 v98, v198, v98
	v_add_f32_e32 v98, v200, v98
	v_add_f32_e32 v98, v202, v98
	v_add_f32_e32 v98, v222, v98
	v_add_f32_e32 v98, v224, v98
	s_waitcnt lgkmcnt(2)
	v_mfma_f32_32x32x16_bf16 v[66:81], v[130:133], v[118:121], v[236:251]
	v_add_f32_e32 v98, v227, v98
	ds_read_b128 v[126:129], v188 offset:32768
	ds_read_b128 v[142:145], v188 offset:40960
	ds_read_b128 v[146:149], v189 offset:32768
	ds_read_b128 v[154:157], v189 offset:40960
	v_add_f32_e32 v98, v229, v98
	v_add_f32_e32 v98, v213, v98
	v_add_f32_e32 v98, v215, v98
	v_add_f32_e32 v98, v217, v98
	v_add_f32_e32 v98, v221, v98
	s_waitcnt lgkmcnt(5)
	v_mfma_f32_32x32x16_bf16 v[82:97], v[134:137], v[114:117], v[82:97]
	v_add_f32_e32 v98, v205, v98
	v_add_f32_e32 v98, v207, v98
	v_add_f32_e32 v98, v209, v98
	v_add_f32_e32 v98, v211, v98
	v_add_f32_e32 v98, v197, v98
	v_add_f32_e32 v98, v199, v98
	v_add_f32_e32 v98, v201, v98
	s_waitcnt lgkmcnt(4)
	v_mfma_f32_32x32x16_bf16 v[66:81], v[138:141], v[114:117], v[66:81]
	v_add_f32_e32 v98, v203, v98
	v_add_f32_e32 v98, v223, v98
	v_add_f32_e32 v98, v226, v98
	v_add_f32_e32 v98, v228, v98
	v_add_f32_e32 v98, v230, v98
	s_waitcnt lgkmcnt(3)
	v_mfma_f32_32x32x16_bf16 v[82:97], v[126:129], v[110:113], v[82:97]
	v_cvt_pk_bf16_f32 v150, v212, v214
	v_cvt_pk_bf16_f32 v151, v216, v218
	v_cvt_pk_bf16_f32 v152, v204, v206
	v_cvt_pk_bf16_f32 v153, v208, v210
	v_cvt_pk_bf16_f32 v134, v196, v198
	v_cvt_pk_bf16_f32 v135, v200, v202
	v_cvt_pk_bf16_f32 v136, v222, v224
	s_waitcnt lgkmcnt(2)
	v_mfma_f32_32x32x16_bf16 v[66:81], v[142:145], v[110:113], v[66:81]
	v_cvt_pk_bf16_f32 v137, v227, v229
	v_cvt_pk_bf16_f32 v130, v213, v215
	v_cvt_pk_bf16_f32 v131, v217, v221
	v_cvt_pk_bf16_f32 v132, v205, v207
	v_cvt_pk_bf16_f32 v133, v209, v211
	v_cvt_pk_bf16_f32 v126, v197, v199
	v_cvt_pk_bf16_f32 v127, v201, v203
	s_waitcnt lgkmcnt(1)
	v_mfma_f32_32x32x16_bf16 v[82:97], v[146:149], v[106:109], v[82:97]
	v_cvt_pk_bf16_f32 v128, v223, v226
	v_cvt_pk_bf16_f32 v129, v228, v230
	s_waitcnt lgkmcnt(0)
	v_mfma_f32_32x32x16_bf16 v[66:81], v[154:157], v[106:109], v[66:81]
	s_add_u32 s100, s12, 0xa0000
	s_addc_u32 s101, s13, 0
	global_load_dwordx4 v[138:141], v160, s[100:101] offset:2048
	global_load_dwordx4 v[142:145], v252, s[100:101]
	global_load_dwordx4 v[154:157], v161, s[100:101] offset:2048
	s_add_u32 s12, s12, 0x140000
	s_addc_u32 s13, s13, 0
	s_and_saveexec_b64 s[2:3], s[8:9]
	s_cbranch_execz .LBB0_345
	ds_read2_b32 v[196:197], v194 offset0:64 offset1:65
	ds_read2_b32 v[198:199], v194 offset0:80 offset1:81
	ds_read2_b32 v[200:201], v194 offset0:82 offset1:83
	ds_read2_b32 v[202:203], v194 offset0:88 offset1:89
	ds_read2_b32 v[204:205], v194 offset0:90 offset1:91
	ds_read2_b32 v[206:207], v194 offset0:66 offset1:67
	ds_read2_b32 v[208:209], v194 offset0:72 offset1:73
	ds_read2_b32 v[210:211], v194 offset0:74 offset1:75
	s_waitcnt lgkmcnt(7)
	v_pk_add_f32 v[82:83], v[82:83], v[196:197]
	s_waitcnt lgkmcnt(3)
	v_pk_add_f32 v[96:97], v[96:97], v[204:205]
	v_pk_add_f32 v[94:95], v[94:95], v[202:203]
	v_pk_add_f32 v[92:93], v[92:93], v[200:201]
	v_pk_add_f32 v[90:91], v[90:91], v[198:199]
	s_waitcnt lgkmcnt(0)
	v_pk_add_f32 v[88:89], v[88:89], v[210:211]
	v_pk_add_f32 v[86:87], v[86:87], v[208:209]
	v_pk_add_f32 v[84:85], v[84:85], v[206:207]
	ds_read2_b32 v[196:197], v194 offset0:112 offset1:113
	ds_read2_b32 v[198:199], v194 offset0:114 offset1:115
	ds_read2_b32 v[200:201], v194 offset0:120 offset1:121
	ds_read2_b32 v[202:203], v194 offset0:122 offset1:123
	ds_read2_b32 v[204:205], v194 offset0:96 offset1:97
	ds_read2_b32 v[206:207], v194 offset0:98 offset1:99
	ds_read2_b32 v[208:209], v194 offset0:104 offset1:105
	ds_read2_b32 v[210:211], v194 offset0:106 offset1:107
	s_waitcnt lgkmcnt(4)
	v_pk_add_f32 v[80:81], v[80:81], v[202:203]
	v_pk_add_f32 v[78:79], v[78:79], v[200:201]
	v_pk_add_f32 v[76:77], v[76:77], v[198:199]
	v_pk_add_f32 v[74:75], v[74:75], v[196:197]
	s_waitcnt lgkmcnt(0)
	v_pk_add_f32 v[72:73], v[72:73], v[210:211]
	v_pk_add_f32 v[70:71], v[70:71], v[208:209]
	v_pk_add_f32 v[68:69], v[68:69], v[206:207]
	v_pk_add_f32 v[66:67], v[66:67], v[204:205]
	s_branch .LBB0_345
